# GA loop: finer MFMA/exp interleave - first column split by k-half so only 8 exps precede the first MFMA
# speedup vs baseline: 1.0025x; 1.0014x over previous
.LBB0_1280:
	v_mov_b64_e32 v[118:119], v[124:125]
	v_exp_f32_e32 v94, v94
	v_exp_f32_e32 v95, v95
	v_exp_f32_e32 v96, v96
	v_exp_f32_e32 v97, v97
	v_exp_f32_e32 v90, v90
	v_exp_f32_e32 v91, v91
	v_exp_f32_e32 v92, v92
	v_exp_f32_e32 v93, v93
	v_cvt_pk_bf16_f32 v160, v94, v95
	v_cvt_pk_bf16_f32 v161, v96, v97
	v_cvt_pk_bf16_f32 v162, v90, v91
	v_cvt_pk_bf16_f32 v163, v92, v93
	s_setprio 1
	s_waitcnt vmcnt(4)
	ds_write_b128 v180, v[58:61] offset:17408
	ds_write_b128 v182, v[62:65] offset:25600
	ds_write_b128 v181, v[66:69] offset:17408
	ds_write_b128 v182, v[70:73] offset:30208
	ds_read2_b64 v[94:97], v176 offset0:64 offset1:68
	v_mfma_f32_16x16x32_bf16 v[38:41], v[190:193], v[160:163], v[38:41]
	v_exp_f32_e32 v102, v102
	v_exp_f32_e32 v103, v103
	v_mfma_f32_16x16x32_bf16 v[30:33], v[212:215], v[160:163], v[30:33]
	v_exp_f32_e32 v104, v104
	v_exp_f32_e32 v105, v105
	v_mfma_f32_16x16x32_bf16 v[22:25], v[244:247], v[160:163], v[22:25]
	v_exp_f32_e32 v98, v98
	v_exp_f32_e32 v99, v99
	s_waitcnt lgkmcnt(0)
	v_mfma_f32_16x16x32_bf16 v[10:13], v[94:97], v[160:163], v[10:13]
	v_exp_f32_e32 v100, v100
	v_exp_f32_e32 v101, v101
	v_cvt_pk_bf16_f32 v166, v102, v103
	v_cvt_pk_bf16_f32 v167, v104, v105
	v_cvt_pk_bf16_f32 v168, v98, v99
	v_cvt_pk_bf16_f32 v169, v100, v101
	ds_read2_b64 v[98:101], v176 offset0:72 offset1:76
	ds_read2_b64 v[102:105], v177 offset0:96 offset1:100
	v_mfma_f32_16x16x32_bf16 v[38:41], v[190:193], v[166:169], v[38:41]
	v_exp_f32_e32 v134, v74
	v_exp_f32_e32 v135, v75
	v_mfma_f32_16x16x32_bf16 v[30:33], v[216:219], v[166:169], v[30:33]
	v_exp_f32_e32 v136, v76
	v_exp_f32_e32 v137, v77
	v_mfma_f32_16x16x32_bf16 v[22:25], v[248:251], v[166:169], v[22:25]
	v_exp_f32_e32 v138, v86
	v_exp_f32_e32 v139, v87
	s_waitcnt lgkmcnt(0)
	v_mfma_f32_16x16x32_bf16 v[6:9], v[102:105], v[160:163], v[6:9]
	v_exp_f32_e32 v140, v88
	v_exp_f32_e32 v141, v89
	v_mfma_f32_16x16x32_bf16 v[10:13], v[98:101], v[166:169], v[10:13]
	v_exp_f32_e32 v122, v78
	v_exp_f32_e32 v123, v79
	v_cvt_pk_bf16_f32 v88, v134, v135
	v_cvt_pk_bf16_f32 v89, v136, v137
	ds_read2_b64 v[134:137], v177 offset0:104 offset1:108
	v_exp_f32_e32 v124, v80
	v_exp_f32_e32 v133, v81
	v_cvt_pk_bf16_f32 v86, v122, v123
	v_cvt_pk_bf16_f32 v87, v124, v133
	s_nop 1
	v_mfma_f32_16x16x32_bf16 v[34:37], v[190:193], v[86:89], v[34:37]
	v_exp_f32_e32 v142, v82
	v_exp_f32_e32 v143, v83
	v_mfma_f32_16x16x32_bf16 v[26:29], v[212:215], v[86:89], v[26:29]
	v_exp_f32_e32 v144, v84
	v_exp_f32_e32 v125, v85
	v_mfma_f32_16x16x32_bf16 v[18:21], v[244:247], v[86:89], v[18:21]
	v_cvt_pk_bf16_f32 v90, v138, v139
	v_cvt_pk_bf16_f32 v91, v140, v141
	v_mfma_f32_16x16x32_bf16 v[14:17], v[94:97], v[86:89], v[14:17]
	v_cvt_pk_bf16_f32 v92, v142, v143
	v_cvt_pk_bf16_f32 v93, v144, v125
	v_mfma_f32_16x16x32_bf16 v[2:5], v[102:105], v[86:89], v[2:5]
	s_nop 0
	v_mfma_f32_16x16x32_bf16 v[34:37], v[190:193], v[90:93], v[34:37]
	v_mfma_f32_16x16x32_bf16 v[26:29], v[216:219], v[90:93], v[26:29]
	v_mfma_f32_16x16x32_bf16 v[18:21], v[248:251], v[90:93], v[18:21]
	v_mfma_f32_16x16x32_bf16 v[14:17], v[98:101], v[90:93], v[14:17]
	s_waitcnt lgkmcnt(0)
	v_mfma_f32_16x16x32_bf16 v[6:9], v[134:137], v[166:169], v[6:9]
	v_mfma_f32_16x16x32_bf16 v[2:5], v[134:137], v[90:93], v[2:5]
	s_setprio 0
	s_cmpk_lg_i32 s0, 0x43
	s_waitcnt lgkmcnt(0)
	s_barrier
	s_cbranch_scc0 .LBB0_1282
	v_mov_b64_e32 v[122:123], v[118:119]
	s_branch .Lga_odd

.Lga_o_1280:
	v_mov_b64_e32 v[118:119], v[124:125]
	v_exp_f32_e32 v94, v94
	v_exp_f32_e32 v95, v95
	v_exp_f32_e32 v96, v96
	v_exp_f32_e32 v97, v97
	v_exp_f32_e32 v90, v90
	v_exp_f32_e32 v91, v91
	v_exp_f32_e32 v92, v92
	v_exp_f32_e32 v93, v93
	v_cvt_pk_bf16_f32 v160, v94, v95
	v_cvt_pk_bf16_f32 v161, v96, v97
	v_cvt_pk_bf16_f32 v162, v90, v91
	v_cvt_pk_bf16_f32 v163, v92, v93
	s_setprio 1
	s_waitcnt vmcnt(4)
	ds_write_b128 v180, v[228:231]
	ds_write_b128 v182, v[232:235] offset:8192
	ds_write_b128 v181, v[236:239]
	ds_write_b128 v182, v[240:243] offset:12800
	ds_read2_b64 v[94:97], v178 offset0:64 offset1:68
	v_mfma_f32_16x16x32_bf16 v[38:41], v[190:193], v[160:163], v[38:41]
	v_exp_f32_e32 v102, v102
	v_exp_f32_e32 v103, v103
	v_mfma_f32_16x16x32_bf16 v[30:33], v[212:215], v[160:163], v[30:33]
	v_exp_f32_e32 v104, v104
	v_exp_f32_e32 v105, v105
	v_mfma_f32_16x16x32_bf16 v[22:25], v[244:247], v[160:163], v[22:25]
	v_exp_f32_e32 v98, v98
	v_exp_f32_e32 v99, v99
	s_waitcnt lgkmcnt(0)
	v_mfma_f32_16x16x32_bf16 v[10:13], v[94:97], v[160:163], v[10:13]
	v_exp_f32_e32 v100, v100
	v_exp_f32_e32 v101, v101
	v_cvt_pk_bf16_f32 v166, v102, v103
	v_cvt_pk_bf16_f32 v167, v104, v105
	v_cvt_pk_bf16_f32 v168, v98, v99
	v_cvt_pk_bf16_f32 v169, v100, v101
	ds_read2_b64 v[98:101], v178 offset0:72 offset1:76
	ds_read2_b64 v[102:105], v179 offset0:96 offset1:100
	v_mfma_f32_16x16x32_bf16 v[38:41], v[190:193], v[166:169], v[38:41]
	v_exp_f32_e32 v134, v74
	v_exp_f32_e32 v135, v75
	v_mfma_f32_16x16x32_bf16 v[30:33], v[216:219], v[166:169], v[30:33]
	v_exp_f32_e32 v136, v76
	v_exp_f32_e32 v137, v77
	v_mfma_f32_16x16x32_bf16 v[22:25], v[248:251], v[166:169], v[22:25]
	v_exp_f32_e32 v138, v86
	v_exp_f32_e32 v139, v87
	s_waitcnt lgkmcnt(0)
	v_mfma_f32_16x16x32_bf16 v[6:9], v[102:105], v[160:163], v[6:9]
	v_exp_f32_e32 v140, v88
	v_exp_f32_e32 v141, v89
	v_mfma_f32_16x16x32_bf16 v[10:13], v[98:101], v[166:169], v[10:13]
	v_exp_f32_e32 v122, v78
	v_exp_f32_e32 v123, v79
	v_cvt_pk_bf16_f32 v88, v134, v135
	v_cvt_pk_bf16_f32 v89, v136, v137
	ds_read2_b64 v[134:137], v179 offset0:104 offset1:108
	v_exp_f32_e32 v124, v80
	v_exp_f32_e32 v133, v81
	v_cvt_pk_bf16_f32 v86, v122, v123
	v_cvt_pk_bf16_f32 v87, v124, v133
	s_nop 1
	v_mfma_f32_16x16x32_bf16 v[34:37], v[190:193], v[86:89], v[34:37]
	v_exp_f32_e32 v142, v82
	v_exp_f32_e32 v143, v83
	v_mfma_f32_16x16x32_bf16 v[26:29], v[212:215], v[86:89], v[26:29]
	v_exp_f32_e32 v144, v84
	v_exp_f32_e32 v125, v85
	v_mfma_f32_16x16x32_bf16 v[18:21], v[244:247], v[86:89], v[18:21]
	v_cvt_pk_bf16_f32 v90, v138, v139
	v_cvt_pk_bf16_f32 v91, v140, v141
	v_mfma_f32_16x16x32_bf16 v[14:17], v[94:97], v[86:89], v[14:17]
	v_cvt_pk_bf16_f32 v92, v142, v143
	v_cvt_pk_bf16_f32 v93, v144, v125
	v_mfma_f32_16x16x32_bf16 v[2:5], v[102:105], v[86:89], v[2:5]
	s_nop 0
	v_mfma_f32_16x16x32_bf16 v[34:37], v[190:193], v[90:93], v[34:37]
	v_mfma_f32_16x16x32_bf16 v[26:29], v[216:219], v[90:93], v[26:29]
	v_mfma_f32_16x16x32_bf16 v[18:21], v[248:251], v[90:93], v[18:21]
	v_mfma_f32_16x16x32_bf16 v[14:17], v[98:101], v[90:93], v[14:17]
	s_waitcnt lgkmcnt(0)
	v_mfma_f32_16x16x32_bf16 v[6:9], v[134:137], v[166:169], v[6:9]
	v_mfma_f32_16x16x32_bf16 v[2:5], v[134:137], v[90:93], v[2:5]
	s_setprio 0
	s_cmpk_lg_i32 s0, 0x43
	s_waitcnt lgkmcnt(0)
	s_barrier
	s_cbranch_scc0 .LBB0_1282
	v_mov_b64_e32 v[122:123], v[118:119]
	s_branch .LBB0_1275
